# EpiGU256: v_permlane16_swap pairs rows m/m+16 -> 8 global_store_dwordx4 instead of 16 dwordx2 per wave and tile
# speedup vs baseline: 1.0148x; 1.0125x over previous
.LBB0_734:
	v_mul_f32_e32 v156, 0xbfb8aa3b, v124
	v_mul_f32_e32 v157, 0xbfb8aa3b, v125
	v_exp_f32_e32 v156, v156
	v_exp_f32_e32 v157, v157
	v_add_u32_e32 v158, s28, v150
	v_ashrrev_i32_e32 v154, 1, v158
	v_add_f32_e32 v156, 1.0, v156
	v_add_f32_e32 v157, 1.0, v157
	v_rcp_f32_e32 v156, v156
	v_rcp_f32_e32 v157, v157
	v_add_u32_e32 v153, s29, v133
	v_ashrrev_i32_e32 v155, 31, v154
	s_movk_i32 s15, 0x1600
	v_pk_mul_f32 v[124:125], v[124:125], v[156:157]
	v_mad_i64_i32 v[148:149], s[28:29], v153, s15, v[136:137]
	v_pk_mul_f32 v[120:121], v[120:121], v[124:125]
	v_mul_f32_e32 v124, 0xbfb8aa3b, v126
	v_mul_f32_e32 v125, 0xbfb8aa3b, v127
	v_exp_f32_e32 v124, v124
	v_exp_f32_e32 v125, v125
	v_add_u32_e32 v142, 16, v153
	v_mad_i64_i32 v[146:147], s[28:29], v142, s15, v[136:137]
	v_add_f32_e32 v124, 1.0, v124
	v_add_f32_e32 v125, 1.0, v125
	v_rcp_f32_e32 v124, v124
	v_rcp_f32_e32 v125, v125
	v_add_u32_e32 v142, 32, v153
	v_mad_i64_i32 v[144:145], s[28:29], v142, s15, v[136:137]
	v_pk_mul_f32 v[124:125], v[126:127], v[124:125]
	v_add_u32_e32 v142, 48, v153
	v_pk_mul_f32 v[122:123], v[122:123], v[124:125]
	v_cvt_pk_bf16_f32 v208, v120, v121
	v_lshlrev_b64 v[120:121], 1, v[154:155]
	v_bfe_u32 v244, v131, 4, 1
	v_mul_u32_u24_e32 v244, 0x15ff8, v244
	v_mov_b32_e32 v245, 0
	v_lshl_add_u64 v[240:241], v[120:121], 0, v[244:245]
	v_cvt_pk_bf16_f32 v209, v122, v123
	v_mul_f32_e32 v122, 0xbfb8aa3b, v116
	v_mul_f32_e32 v123, 0xbfb8aa3b, v117
	v_exp_f32_e32 v122, v122
	v_exp_f32_e32 v123, v123
	v_mad_i64_i32 v[142:143], s[28:29], v142, s15, v[136:137]
	v_add_f32_e32 v122, 1.0, v122
	v_add_f32_e32 v123, 1.0, v123
	v_rcp_f32_e32 v122, v122
	v_rcp_f32_e32 v123, v123
	s_andn2_b64 vcc, exec, s[12:13]
	v_pk_mul_f32 v[116:117], v[116:117], v[122:123]
	s_nop 0
	v_pk_mul_f32 v[112:113], v[112:113], v[116:117]
	v_mul_f32_e32 v116, 0xbfb8aa3b, v118
	v_mul_f32_e32 v117, 0xbfb8aa3b, v119
	v_exp_f32_e32 v116, v116
	v_exp_f32_e32 v117, v117
	v_cvt_pk_bf16_f32 v210, v112, v113
	v_add_f32_e32 v116, 1.0, v116
	v_add_f32_e32 v117, 1.0, v117
	v_rcp_f32_e32 v116, v116
	v_rcp_f32_e32 v117, v117
	s_nop 0
	v_pk_mul_f32 v[116:117], v[118:119], v[116:117]
	s_nop 0
	v_pk_mul_f32 v[114:115], v[114:115], v[116:117]
	s_nop 0
	v_cvt_pk_bf16_f32 v211, v114, v115
	v_lshl_add_u64 v[114:115], v[148:149], 0, v[240:241]
	s_nop 1
	v_permlane16_swap_b32 v208, v210
	v_permlane16_swap_b32 v209, v211
	global_store_dwordx4 v[114:115], v[208:211], off
	v_mul_f32_e32 v112, 0xbfb8aa3b, v108
	v_mul_f32_e32 v113, 0xbfb8aa3b, v109
	v_exp_f32_e32 v112, v112
	v_exp_f32_e32 v113, v113
	v_add_f32_e32 v112, 1.0, v112
	v_add_f32_e32 v113, 1.0, v113
	v_rcp_f32_e32 v112, v112
	v_rcp_f32_e32 v113, v113
	s_nop 0
	v_pk_mul_f32 v[108:109], v[108:109], v[112:113]
	s_nop 0
	v_pk_mul_f32 v[104:105], v[104:105], v[108:109]
	v_mul_f32_e32 v108, 0xbfb8aa3b, v110
	v_mul_f32_e32 v109, 0xbfb8aa3b, v111
	v_exp_f32_e32 v108, v108
	v_exp_f32_e32 v109, v109
	v_cvt_pk_bf16_f32 v212, v104, v105
	v_add_f32_e32 v108, 1.0, v108
	v_add_f32_e32 v109, 1.0, v109
	v_rcp_f32_e32 v108, v108
	v_rcp_f32_e32 v109, v109
	s_nop 0
	v_pk_mul_f32 v[108:109], v[110:111], v[108:109]
	s_nop 0
	v_pk_mul_f32 v[106:107], v[106:107], v[108:109]
	s_nop 0
	v_cvt_pk_bf16_f32 v213, v106, v107
	v_mul_f32_e32 v104, 0xbfb8aa3b, v100
	v_mul_f32_e32 v105, 0xbfb8aa3b, v101
	v_exp_f32_e32 v104, v104
	v_exp_f32_e32 v105, v105
	v_add_f32_e32 v104, 1.0, v104
	v_add_f32_e32 v105, 1.0, v105
	v_rcp_f32_e32 v104, v104
	v_rcp_f32_e32 v105, v105
	s_nop 0
	v_pk_mul_f32 v[100:101], v[100:101], v[104:105]
	s_nop 0
	v_pk_mul_f32 v[96:97], v[96:97], v[100:101]
	v_mul_f32_e32 v100, 0xbfb8aa3b, v102
	v_mul_f32_e32 v101, 0xbfb8aa3b, v103
	v_exp_f32_e32 v100, v100
	v_exp_f32_e32 v101, v101
	v_cvt_pk_bf16_f32 v214, v96, v97
	v_add_f32_e32 v100, 1.0, v100
	v_add_f32_e32 v101, 1.0, v101
	v_rcp_f32_e32 v100, v100
	v_rcp_f32_e32 v101, v101
	s_nop 0
	v_pk_mul_f32 v[100:101], v[102:103], v[100:101]
	s_nop 0
	v_pk_mul_f32 v[98:99], v[98:99], v[100:101]
	s_nop 0
	v_cvt_pk_bf16_f32 v215, v98, v99
	v_lshl_add_u64 v[98:99], v[144:145], 0, v[240:241]
	s_nop 1
	v_permlane16_swap_b32 v212, v214
	v_permlane16_swap_b32 v213, v215
	global_store_dwordx4 v[98:99], v[212:215], off
	v_mul_f32_e32 v98, 0xbfb8aa3b, v92
	v_mul_f32_e32 v99, 0xbfb8aa3b, v93
	v_exp_f32_e32 v98, v98
	v_exp_f32_e32 v99, v99
	v_add_u32_e32 v96, 0x80, v158
	v_ashrrev_i32_e32 v96, 1, v96
	v_add_f32_e32 v98, 1.0, v98
	v_add_f32_e32 v99, 1.0, v99
	v_rcp_f32_e32 v98, v98
	v_rcp_f32_e32 v99, v99
	v_ashrrev_i32_e32 v97, 31, v96
	v_pk_mul_f32 v[92:93], v[92:93], v[98:99]
	s_nop 0
	v_pk_mul_f32 v[88:89], v[88:89], v[92:93]
	v_mul_f32_e32 v92, 0xbfb8aa3b, v94
	v_mul_f32_e32 v93, 0xbfb8aa3b, v95
	v_exp_f32_e32 v92, v92
	v_exp_f32_e32 v93, v93
	v_add_f32_e32 v92, 1.0, v92
	v_add_f32_e32 v93, 1.0, v93
	v_rcp_f32_e32 v92, v92
	v_rcp_f32_e32 v93, v93
	s_nop 0
	v_pk_mul_f32 v[92:93], v[94:95], v[92:93]
	s_nop 0
	v_pk_mul_f32 v[90:91], v[90:91], v[92:93]
	v_cvt_pk_bf16_f32 v216, v88, v89
	v_lshlrev_b64 v[88:89], 1, v[96:97]
	v_lshl_add_u64 v[242:243], v[88:89], 0, v[244:245]
	v_cvt_pk_bf16_f32 v217, v90, v91
	v_mul_f32_e32 v90, 0xbfb8aa3b, v84
	v_mul_f32_e32 v91, 0xbfb8aa3b, v85
	v_exp_f32_e32 v90, v90
	v_exp_f32_e32 v91, v91
	v_add_f32_e32 v90, 1.0, v90
	v_add_f32_e32 v91, 1.0, v91
	v_rcp_f32_e32 v90, v90
	v_rcp_f32_e32 v91, v91
	s_nop 0
	v_pk_mul_f32 v[84:85], v[84:85], v[90:91]
	s_nop 0
	v_pk_mul_f32 v[80:81], v[80:81], v[84:85]
	v_mul_f32_e32 v84, 0xbfb8aa3b, v86
	v_mul_f32_e32 v85, 0xbfb8aa3b, v87
	v_exp_f32_e32 v84, v84
	v_exp_f32_e32 v85, v85
	v_cvt_pk_bf16_f32 v218, v80, v81
	v_add_f32_e32 v84, 1.0, v84
	v_add_f32_e32 v85, 1.0, v85
	v_rcp_f32_e32 v84, v84
	v_rcp_f32_e32 v85, v85
	s_nop 0
	v_pk_mul_f32 v[84:85], v[86:87], v[84:85]
	s_nop 0
	v_pk_mul_f32 v[82:83], v[82:83], v[84:85]
	s_nop 0
	v_cvt_pk_bf16_f32 v219, v82, v83
	v_lshl_add_u64 v[82:83], v[148:149], 0, v[242:243]
	s_nop 1
	v_permlane16_swap_b32 v216, v218
	v_permlane16_swap_b32 v217, v219
	global_store_dwordx4 v[82:83], v[216:219], off
	v_mul_f32_e32 v80, 0xbfb8aa3b, v76
	v_mul_f32_e32 v81, 0xbfb8aa3b, v77
	v_exp_f32_e32 v80, v80
	v_exp_f32_e32 v81, v81
	v_add_f32_e32 v80, 1.0, v80
	v_add_f32_e32 v81, 1.0, v81
	v_rcp_f32_e32 v80, v80
	v_rcp_f32_e32 v81, v81
	s_nop 0
	v_pk_mul_f32 v[76:77], v[76:77], v[80:81]
	s_nop 0
	v_pk_mul_f32 v[72:73], v[72:73], v[76:77]
	v_mul_f32_e32 v76, 0xbfb8aa3b, v78
	v_mul_f32_e32 v77, 0xbfb8aa3b, v79
	v_exp_f32_e32 v76, v76
	v_exp_f32_e32 v77, v77
	v_cvt_pk_bf16_f32 v220, v72, v73
	v_add_f32_e32 v76, 1.0, v76
	v_add_f32_e32 v77, 1.0, v77
	v_rcp_f32_e32 v76, v76
	v_rcp_f32_e32 v77, v77
	s_nop 0
	v_pk_mul_f32 v[76:77], v[78:79], v[76:77]
	s_nop 0
	v_pk_mul_f32 v[74:75], v[74:75], v[76:77]
	s_nop 0
	v_cvt_pk_bf16_f32 v221, v74, v75
	v_mul_f32_e32 v72, 0xbfb8aa3b, v68
	v_mul_f32_e32 v73, 0xbfb8aa3b, v69
	v_exp_f32_e32 v72, v72
	v_exp_f32_e32 v73, v73
	v_add_f32_e32 v72, 1.0, v72
	v_add_f32_e32 v73, 1.0, v73
	v_rcp_f32_e32 v72, v72
	v_rcp_f32_e32 v73, v73
	s_nop 0
	v_pk_mul_f32 v[68:69], v[68:69], v[72:73]
	v_mul_f32_e32 v72, 0xbfb8aa3b, v60
	v_mul_f32_e32 v73, 0xbfb8aa3b, v61
	v_exp_f32_e32 v72, v72
	v_exp_f32_e32 v73, v73
	v_pk_mul_f32 v[64:65], v[64:65], v[68:69]
	v_mul_f32_e32 v68, 0xbfb8aa3b, v70
	v_add_f32_e32 v72, 1.0, v72
	v_add_f32_e32 v73, 1.0, v73
	v_rcp_f32_e32 v72, v72
	v_rcp_f32_e32 v73, v73
	v_mul_f32_e32 v69, 0xbfb8aa3b, v71
	v_exp_f32_e32 v68, v68
	v_exp_f32_e32 v69, v69
	v_pk_mul_f32 v[60:61], v[60:61], v[72:73]
	v_cvt_pk_bf16_f32 v222, v64, v65
	v_pk_mul_f32 v[56:57], v[56:57], v[60:61]
	v_mul_f32_e32 v60, 0xbfb8aa3b, v62
	v_mul_f32_e32 v61, 0xbfb8aa3b, v63
	v_exp_f32_e32 v60, v60
	v_exp_f32_e32 v61, v61
	v_add_f32_e32 v68, 1.0, v68
	v_add_f32_e32 v69, 1.0, v69
	v_rcp_f32_e32 v68, v68
	v_rcp_f32_e32 v69, v69
	v_add_f32_e32 v60, 1.0, v60
	v_add_f32_e32 v61, 1.0, v61
	v_rcp_f32_e32 v60, v60
	v_rcp_f32_e32 v61, v61
	v_pk_mul_f32 v[68:69], v[70:71], v[68:69]
	v_cvt_pk_bf16_f32 v224, v56, v57
	v_pk_mul_f32 v[66:67], v[66:67], v[68:69]
	v_pk_mul_f32 v[60:61], v[62:63], v[60:61]
	v_cvt_pk_bf16_f32 v223, v66, v67
	v_lshl_add_u64 v[66:67], v[144:145], 0, v[242:243]
	s_nop 1
	v_permlane16_swap_b32 v220, v222
	v_permlane16_swap_b32 v221, v223
	global_store_dwordx4 v[66:67], v[220:223], off
	v_add_u32_e32 v64, 0x80, v153
	v_mad_i64_i32 v[70:71], s[28:29], v64, s15, v[136:137]
	v_pk_mul_f32 v[58:59], v[58:59], v[60:61]
	v_add_u32_e32 v64, 0x90, v153
	v_cvt_pk_bf16_f32 v225, v58, v59
	v_mul_f32_e32 v56, 0xbfb8aa3b, v52
	v_mul_f32_e32 v57, 0xbfb8aa3b, v53
	v_exp_f32_e32 v56, v56
	v_exp_f32_e32 v57, v57
	v_mad_i64_i32 v[68:69], s[28:29], v64, s15, v[136:137]
	v_add_f32_e32 v56, 1.0, v56
	v_add_f32_e32 v57, 1.0, v57
	v_rcp_f32_e32 v56, v56
	v_rcp_f32_e32 v57, v57
	v_add_u32_e32 v64, 0xa0, v153
	v_mad_i64_i32 v[66:67], s[28:29], v64, s15, v[136:137]
	v_pk_mul_f32 v[52:53], v[52:53], v[56:57]
	v_add_u32_e32 v64, 0xb0, v153
	v_pk_mul_f32 v[48:49], v[48:49], v[52:53]
	v_mul_f32_e32 v52, 0xbfb8aa3b, v54
	v_mul_f32_e32 v53, 0xbfb8aa3b, v55
	v_exp_f32_e32 v52, v52
	v_exp_f32_e32 v53, v53
	v_cvt_pk_bf16_f32 v226, v48, v49
	v_mad_i64_i32 v[64:65], s[28:29], v64, s15, v[136:137]
	v_add_f32_e32 v52, 1.0, v52
	v_add_f32_e32 v53, 1.0, v53
	v_rcp_f32_e32 v52, v52
	v_rcp_f32_e32 v53, v53
	s_mov_b32 s28, s16
	s_mov_b32 s29, s14
	v_pk_mul_f32 v[52:53], v[54:55], v[52:53]
	s_nop 0
	v_pk_mul_f32 v[50:51], v[50:51], v[52:53]
	s_nop 0
	v_cvt_pk_bf16_f32 v227, v50, v51
	v_lshl_add_u64 v[50:51], v[70:71], 0, v[240:241]
	s_nop 1
	v_permlane16_swap_b32 v224, v226
	v_permlane16_swap_b32 v225, v227
	global_store_dwordx4 v[50:51], v[224:227], off
	v_mul_f32_e32 v48, 0xbfb8aa3b, v44
	v_mul_f32_e32 v49, 0xbfb8aa3b, v45
	v_exp_f32_e32 v48, v48
	v_exp_f32_e32 v49, v49
	v_add_f32_e32 v48, 1.0, v48
	v_add_f32_e32 v49, 1.0, v49
	v_rcp_f32_e32 v48, v48
	v_rcp_f32_e32 v49, v49
	s_nop 0
	v_pk_mul_f32 v[44:45], v[44:45], v[48:49]
	s_nop 0
	v_pk_mul_f32 v[40:41], v[40:41], v[44:45]
	v_mul_f32_e32 v44, 0xbfb8aa3b, v46
	v_mul_f32_e32 v45, 0xbfb8aa3b, v47
	v_exp_f32_e32 v44, v44
	v_exp_f32_e32 v45, v45
	v_cvt_pk_bf16_f32 v228, v40, v41
	v_add_f32_e32 v44, 1.0, v44
	v_add_f32_e32 v45, 1.0, v45
	v_rcp_f32_e32 v44, v44
	v_rcp_f32_e32 v45, v45
	s_nop 0
	v_pk_mul_f32 v[44:45], v[46:47], v[44:45]
	s_nop 0
	v_pk_mul_f32 v[42:43], v[42:43], v[44:45]
	s_nop 0
	v_cvt_pk_bf16_f32 v229, v42, v43
	v_mul_f32_e32 v40, 0xbfb8aa3b, v36
	v_mul_f32_e32 v41, 0xbfb8aa3b, v37
	v_exp_f32_e32 v40, v40
	v_exp_f32_e32 v41, v41
	v_add_f32_e32 v40, 1.0, v40
	v_add_f32_e32 v41, 1.0, v41
	v_rcp_f32_e32 v40, v40
	v_rcp_f32_e32 v41, v41
	s_nop 0
	v_pk_mul_f32 v[36:37], v[36:37], v[40:41]
	s_nop 0
	v_pk_mul_f32 v[32:33], v[32:33], v[36:37]
	v_mul_f32_e32 v36, 0xbfb8aa3b, v38
	v_mul_f32_e32 v37, 0xbfb8aa3b, v39
	v_exp_f32_e32 v36, v36
	v_exp_f32_e32 v37, v37
	v_cvt_pk_bf16_f32 v230, v32, v33
	v_add_f32_e32 v36, 1.0, v36
	v_add_f32_e32 v37, 1.0, v37
	v_rcp_f32_e32 v36, v36
	v_rcp_f32_e32 v37, v37
	s_nop 0
	v_pk_mul_f32 v[36:37], v[38:39], v[36:37]
	s_nop 0
	v_pk_mul_f32 v[34:35], v[34:35], v[36:37]
	s_nop 0
	v_cvt_pk_bf16_f32 v231, v34, v35
	v_lshl_add_u64 v[34:35], v[66:67], 0, v[240:241]
	s_nop 1
	v_permlane16_swap_b32 v228, v230
	v_permlane16_swap_b32 v229, v231
	global_store_dwordx4 v[34:35], v[228:231], off
	v_mul_f32_e32 v32, 0xbfb8aa3b, v28
	v_mul_f32_e32 v33, 0xbfb8aa3b, v29
	v_exp_f32_e32 v32, v32
	v_exp_f32_e32 v33, v33
	v_add_f32_e32 v32, 1.0, v32
	v_add_f32_e32 v33, 1.0, v33
	v_rcp_f32_e32 v32, v32
	v_rcp_f32_e32 v33, v33
	s_nop 0
	v_pk_mul_f32 v[28:29], v[28:29], v[32:33]
	s_nop 0
	v_pk_mul_f32 v[24:25], v[24:25], v[28:29]
	v_mul_f32_e32 v28, 0xbfb8aa3b, v30
	v_mul_f32_e32 v29, 0xbfb8aa3b, v31
	v_exp_f32_e32 v28, v28
	v_exp_f32_e32 v29, v29
	v_cvt_pk_bf16_f32 v232, v24, v25
	v_add_f32_e32 v28, 1.0, v28
	v_add_f32_e32 v29, 1.0, v29
	v_rcp_f32_e32 v28, v28
	v_rcp_f32_e32 v29, v29
	s_nop 0
	v_pk_mul_f32 v[28:29], v[30:31], v[28:29]
	s_nop 0
	v_pk_mul_f32 v[26:27], v[26:27], v[28:29]
	s_nop 0
	v_cvt_pk_bf16_f32 v233, v26, v27
	v_mul_f32_e32 v24, 0xbfb8aa3b, v20
	v_mul_f32_e32 v25, 0xbfb8aa3b, v21
	v_exp_f32_e32 v24, v24
	v_exp_f32_e32 v25, v25
	v_add_f32_e32 v24, 1.0, v24
	v_add_f32_e32 v25, 1.0, v25
	v_rcp_f32_e32 v24, v24
	v_rcp_f32_e32 v25, v25
	s_nop 0
	v_pk_mul_f32 v[20:21], v[20:21], v[24:25]
	s_nop 0
	v_pk_mul_f32 v[16:17], v[16:17], v[20:21]
	v_mul_f32_e32 v20, 0xbfb8aa3b, v22
	v_mul_f32_e32 v21, 0xbfb8aa3b, v23
	v_exp_f32_e32 v20, v20
	v_exp_f32_e32 v21, v21
	v_cvt_pk_bf16_f32 v234, v16, v17
	v_add_f32_e32 v20, 1.0, v20
	v_add_f32_e32 v21, 1.0, v21
	v_rcp_f32_e32 v20, v20
	v_rcp_f32_e32 v21, v21
	s_nop 0
	v_pk_mul_f32 v[20:21], v[22:23], v[20:21]
	s_nop 0
	v_pk_mul_f32 v[18:19], v[18:19], v[20:21]
	s_nop 0
	v_cvt_pk_bf16_f32 v235, v18, v19
	v_lshl_add_u64 v[18:19], v[70:71], 0, v[242:243]
	s_nop 1
	v_permlane16_swap_b32 v232, v234
	v_permlane16_swap_b32 v233, v235
	global_store_dwordx4 v[18:19], v[232:235], off
	v_mul_f32_e32 v16, 0xbfb8aa3b, v12
	v_mul_f32_e32 v17, 0xbfb8aa3b, v13
	v_exp_f32_e32 v16, v16
	v_exp_f32_e32 v17, v17
	v_add_f32_e32 v16, 1.0, v16
	v_add_f32_e32 v17, 1.0, v17
	v_rcp_f32_e32 v16, v16
	v_rcp_f32_e32 v17, v17
	s_nop 0
	v_pk_mul_f32 v[12:13], v[12:13], v[16:17]
	s_nop 0
	v_pk_mul_f32 v[8:9], v[8:9], v[12:13]
	v_mul_f32_e32 v12, 0xbfb8aa3b, v14
	v_mul_f32_e32 v13, 0xbfb8aa3b, v15
	v_exp_f32_e32 v12, v12
	v_exp_f32_e32 v13, v13
	v_cvt_pk_bf16_f32 v236, v8, v9
	v_add_f32_e32 v12, 1.0, v12
	v_add_f32_e32 v13, 1.0, v13
	v_rcp_f32_e32 v12, v12
	v_rcp_f32_e32 v13, v13
	s_nop 0
	v_pk_mul_f32 v[12:13], v[14:15], v[12:13]
	s_nop 0
	v_pk_mul_f32 v[10:11], v[10:11], v[12:13]
	s_nop 0
	v_cvt_pk_bf16_f32 v237, v10, v11
	v_mul_f32_e32 v8, 0xbfb8aa3b, v4
	v_mul_f32_e32 v9, 0xbfb8aa3b, v5
	v_exp_f32_e32 v8, v8
	v_exp_f32_e32 v9, v9
	v_add_f32_e32 v8, 1.0, v8
	v_add_f32_e32 v9, 1.0, v9
	v_rcp_f32_e32 v8, v8
	v_rcp_f32_e32 v9, v9
	s_nop 0
	v_pk_mul_f32 v[4:5], v[4:5], v[8:9]
	s_nop 0
	v_pk_mul_f32 v[0:1], v[0:1], v[4:5]
	v_mul_f32_e32 v4, 0xbfb8aa3b, v6
	v_mul_f32_e32 v5, 0xbfb8aa3b, v7
	v_exp_f32_e32 v4, v4
	v_exp_f32_e32 v5, v5
	v_cvt_pk_bf16_f32 v238, v0, v1
	v_add_f32_e32 v4, 1.0, v4
	v_add_f32_e32 v5, 1.0, v5
	v_rcp_f32_e32 v4, v4
	v_rcp_f32_e32 v5, v5
	s_nop 0
	v_pk_mul_f32 v[4:5], v[6:7], v[4:5]
	s_nop 0
	v_pk_mul_f32 v[2:3], v[2:3], v[4:5]
	s_nop 0
	v_cvt_pk_bf16_f32 v239, v2, v3
	v_lshl_add_u64 v[2:3], v[66:67], 0, v[242:243]
	s_nop 1
	v_permlane16_swap_b32 v236, v238
	v_permlane16_swap_b32 v237, v239
	global_store_dwordx4 v[2:3], v[236:239], off
	s_cbranch_vccz .LBB0_743

.LBB0_1961:
	v_mul_f32_e32 v156, 0xbfb8aa3b, v124
	v_mul_f32_e32 v157, 0xbfb8aa3b, v125
	v_exp_f32_e32 v156, v156
	v_exp_f32_e32 v157, v157
	v_add_u32_e32 v158, s18, v150
	v_ashrrev_i32_e32 v154, 1, v158
	v_add_f32_e32 v156, 1.0, v156
	v_add_f32_e32 v157, 1.0, v157
	v_rcp_f32_e32 v156, v156
	v_rcp_f32_e32 v157, v157
	v_add_u32_e32 v153, s16, v133
	v_ashrrev_i32_e32 v155, 31, v154
	s_movk_i32 s13, 0x1600
	v_pk_mul_f32 v[124:125], v[124:125], v[156:157]
	v_mad_i64_i32 v[148:149], s[34:35], v153, s13, v[136:137]
	v_pk_mul_f32 v[120:121], v[120:121], v[124:125]
	v_mul_f32_e32 v124, 0xbfb8aa3b, v126
	v_mul_f32_e32 v125, 0xbfb8aa3b, v127
	v_exp_f32_e32 v124, v124
	v_exp_f32_e32 v125, v125
	v_add_u32_e32 v142, 16, v153
	v_mad_i64_i32 v[146:147], s[34:35], v142, s13, v[136:137]
	v_add_f32_e32 v124, 1.0, v124
	v_add_f32_e32 v125, 1.0, v125
	v_rcp_f32_e32 v124, v124
	v_rcp_f32_e32 v125, v125
	v_add_u32_e32 v142, 32, v153
	v_mad_i64_i32 v[144:145], s[34:35], v142, s13, v[136:137]
	v_pk_mul_f32 v[124:125], v[126:127], v[124:125]
	v_add_u32_e32 v142, 48, v153
	v_pk_mul_f32 v[122:123], v[122:123], v[124:125]
	v_cvt_pk_bf16_f32 v208, v120, v121
	v_lshlrev_b64 v[120:121], 1, v[154:155]
	v_bfe_u32 v244, v131, 4, 1
	v_mul_u32_u24_e32 v244, 0x15ff8, v244
	v_mov_b32_e32 v245, 0
	v_lshl_add_u64 v[240:241], v[120:121], 0, v[244:245]
	v_cvt_pk_bf16_f32 v209, v122, v123
	v_mul_f32_e32 v122, 0xbfb8aa3b, v116
	v_mul_f32_e32 v123, 0xbfb8aa3b, v117
	v_exp_f32_e32 v122, v122
	v_exp_f32_e32 v123, v123
	v_mad_i64_i32 v[142:143], s[34:35], v142, s13, v[136:137]
	v_add_f32_e32 v122, 1.0, v122
	v_add_f32_e32 v123, 1.0, v123
	v_rcp_f32_e32 v122, v122
	v_rcp_f32_e32 v123, v123
	s_andn2_b64 vcc, exec, s[10:11]
	s_mov_b32 s18, s14
	s_mov_b32 s16, s12
	v_pk_mul_f32 v[116:117], v[116:117], v[122:123]
	s_nop 0
	v_pk_mul_f32 v[112:113], v[112:113], v[116:117]
	v_mul_f32_e32 v116, 0xbfb8aa3b, v118
	v_mul_f32_e32 v117, 0xbfb8aa3b, v119
	v_exp_f32_e32 v116, v116
	v_exp_f32_e32 v117, v117
	v_cvt_pk_bf16_f32 v210, v112, v113
	v_add_f32_e32 v116, 1.0, v116
	v_add_f32_e32 v117, 1.0, v117
	v_rcp_f32_e32 v116, v116
	v_rcp_f32_e32 v117, v117
	s_nop 0
	v_pk_mul_f32 v[116:117], v[118:119], v[116:117]
	s_nop 0
	v_pk_mul_f32 v[114:115], v[114:115], v[116:117]
	s_nop 0
	v_cvt_pk_bf16_f32 v211, v114, v115
	v_lshl_add_u64 v[114:115], v[148:149], 0, v[240:241]
	s_nop 1
	v_permlane16_swap_b32 v208, v210
	v_permlane16_swap_b32 v209, v211
	global_store_dwordx4 v[114:115], v[208:211], off
	v_mul_f32_e32 v112, 0xbfb8aa3b, v108
	v_mul_f32_e32 v113, 0xbfb8aa3b, v109
	v_exp_f32_e32 v112, v112
	v_exp_f32_e32 v113, v113
	v_add_f32_e32 v112, 1.0, v112
	v_add_f32_e32 v113, 1.0, v113
	v_rcp_f32_e32 v112, v112
	v_rcp_f32_e32 v113, v113
	s_nop 0
	v_pk_mul_f32 v[108:109], v[108:109], v[112:113]
	s_nop 0
	v_pk_mul_f32 v[104:105], v[104:105], v[108:109]
	v_mul_f32_e32 v108, 0xbfb8aa3b, v110
	v_mul_f32_e32 v109, 0xbfb8aa3b, v111
	v_exp_f32_e32 v108, v108
	v_exp_f32_e32 v109, v109
	v_cvt_pk_bf16_f32 v212, v104, v105
	v_add_f32_e32 v108, 1.0, v108
	v_add_f32_e32 v109, 1.0, v109
	v_rcp_f32_e32 v108, v108
	v_rcp_f32_e32 v109, v109
	s_nop 0
	v_pk_mul_f32 v[108:109], v[110:111], v[108:109]
	s_nop 0
	v_pk_mul_f32 v[106:107], v[106:107], v[108:109]
	s_nop 0
	v_cvt_pk_bf16_f32 v213, v106, v107
	v_mul_f32_e32 v104, 0xbfb8aa3b, v100
	v_mul_f32_e32 v105, 0xbfb8aa3b, v101
	v_exp_f32_e32 v104, v104
	v_exp_f32_e32 v105, v105
	v_add_f32_e32 v104, 1.0, v104
	v_add_f32_e32 v105, 1.0, v105
	v_rcp_f32_e32 v104, v104
	v_rcp_f32_e32 v105, v105
	s_nop 0
	v_pk_mul_f32 v[100:101], v[100:101], v[104:105]
	s_nop 0
	v_pk_mul_f32 v[96:97], v[96:97], v[100:101]
	v_mul_f32_e32 v100, 0xbfb8aa3b, v102
	v_mul_f32_e32 v101, 0xbfb8aa3b, v103
	v_exp_f32_e32 v100, v100
	v_exp_f32_e32 v101, v101
	v_cvt_pk_bf16_f32 v214, v96, v97
	v_add_f32_e32 v100, 1.0, v100
	v_add_f32_e32 v101, 1.0, v101
	v_rcp_f32_e32 v100, v100
	v_rcp_f32_e32 v101, v101
	s_nop 0
	v_pk_mul_f32 v[100:101], v[102:103], v[100:101]
	s_nop 0
	v_pk_mul_f32 v[98:99], v[98:99], v[100:101]
	s_nop 0
	v_cvt_pk_bf16_f32 v215, v98, v99
	v_lshl_add_u64 v[98:99], v[144:145], 0, v[240:241]
	s_nop 1
	v_permlane16_swap_b32 v212, v214
	v_permlane16_swap_b32 v213, v215
	global_store_dwordx4 v[98:99], v[212:215], off
	v_mul_f32_e32 v98, 0xbfb8aa3b, v92
	v_mul_f32_e32 v99, 0xbfb8aa3b, v93
	v_exp_f32_e32 v98, v98
	v_exp_f32_e32 v99, v99
	v_add_u32_e32 v96, 0x80, v158
	v_ashrrev_i32_e32 v96, 1, v96
	v_add_f32_e32 v98, 1.0, v98
	v_add_f32_e32 v99, 1.0, v99
	v_rcp_f32_e32 v98, v98
	v_rcp_f32_e32 v99, v99
	v_ashrrev_i32_e32 v97, 31, v96
	v_pk_mul_f32 v[92:93], v[92:93], v[98:99]
	s_nop 0
	v_pk_mul_f32 v[88:89], v[88:89], v[92:93]
	v_mul_f32_e32 v92, 0xbfb8aa3b, v94
	v_mul_f32_e32 v93, 0xbfb8aa3b, v95
	v_exp_f32_e32 v92, v92
	v_exp_f32_e32 v93, v93
	v_add_f32_e32 v92, 1.0, v92
	v_add_f32_e32 v93, 1.0, v93
	v_rcp_f32_e32 v92, v92
	v_rcp_f32_e32 v93, v93
	s_nop 0
	v_pk_mul_f32 v[92:93], v[94:95], v[92:93]
	s_nop 0
	v_pk_mul_f32 v[90:91], v[90:91], v[92:93]
	v_cvt_pk_bf16_f32 v216, v88, v89
	v_lshlrev_b64 v[88:89], 1, v[96:97]
	v_lshl_add_u64 v[242:243], v[88:89], 0, v[244:245]
	v_cvt_pk_bf16_f32 v217, v90, v91
	v_mul_f32_e32 v90, 0xbfb8aa3b, v84
	v_mul_f32_e32 v91, 0xbfb8aa3b, v85
	v_exp_f32_e32 v90, v90
	v_exp_f32_e32 v91, v91
	v_add_f32_e32 v90, 1.0, v90
	v_add_f32_e32 v91, 1.0, v91
	v_rcp_f32_e32 v90, v90
	v_rcp_f32_e32 v91, v91
	s_nop 0
	v_pk_mul_f32 v[84:85], v[84:85], v[90:91]
	s_nop 0
	v_pk_mul_f32 v[80:81], v[80:81], v[84:85]
	v_mul_f32_e32 v84, 0xbfb8aa3b, v86
	v_mul_f32_e32 v85, 0xbfb8aa3b, v87
	v_exp_f32_e32 v84, v84
	v_exp_f32_e32 v85, v85
	v_cvt_pk_bf16_f32 v218, v80, v81
	v_add_f32_e32 v84, 1.0, v84
	v_add_f32_e32 v85, 1.0, v85
	v_rcp_f32_e32 v84, v84
	v_rcp_f32_e32 v85, v85
	s_nop 0
	v_pk_mul_f32 v[84:85], v[86:87], v[84:85]
	s_nop 0
	v_pk_mul_f32 v[82:83], v[82:83], v[84:85]
	s_nop 0
	v_cvt_pk_bf16_f32 v219, v82, v83
	v_lshl_add_u64 v[82:83], v[148:149], 0, v[242:243]
	s_nop 1
	v_permlane16_swap_b32 v216, v218
	v_permlane16_swap_b32 v217, v219
	global_store_dwordx4 v[82:83], v[216:219], off
	v_mul_f32_e32 v80, 0xbfb8aa3b, v76
	v_mul_f32_e32 v81, 0xbfb8aa3b, v77
	v_exp_f32_e32 v80, v80
	v_exp_f32_e32 v81, v81
	v_add_f32_e32 v80, 1.0, v80
	v_add_f32_e32 v81, 1.0, v81
	v_rcp_f32_e32 v80, v80
	v_rcp_f32_e32 v81, v81
	s_nop 0
	v_pk_mul_f32 v[76:77], v[76:77], v[80:81]
	s_nop 0
	v_pk_mul_f32 v[72:73], v[72:73], v[76:77]
	v_mul_f32_e32 v76, 0xbfb8aa3b, v78
	v_mul_f32_e32 v77, 0xbfb8aa3b, v79
	v_exp_f32_e32 v76, v76
	v_exp_f32_e32 v77, v77
	v_cvt_pk_bf16_f32 v220, v72, v73
	v_add_f32_e32 v76, 1.0, v76
	v_add_f32_e32 v77, 1.0, v77
	v_rcp_f32_e32 v76, v76
	v_rcp_f32_e32 v77, v77
	s_nop 0
	v_pk_mul_f32 v[76:77], v[78:79], v[76:77]
	s_nop 0
	v_pk_mul_f32 v[74:75], v[74:75], v[76:77]
	s_nop 0
	v_cvt_pk_bf16_f32 v221, v74, v75
	v_mul_f32_e32 v72, 0xbfb8aa3b, v68
	v_mul_f32_e32 v73, 0xbfb8aa3b, v69
	v_exp_f32_e32 v72, v72
	v_exp_f32_e32 v73, v73
	v_add_f32_e32 v72, 1.0, v72
	v_add_f32_e32 v73, 1.0, v73
	v_rcp_f32_e32 v72, v72
	v_rcp_f32_e32 v73, v73
	s_nop 0
	v_pk_mul_f32 v[68:69], v[68:69], v[72:73]
	v_mul_f32_e32 v72, 0xbfb8aa3b, v60
	v_mul_f32_e32 v73, 0xbfb8aa3b, v61
	v_exp_f32_e32 v72, v72
	v_exp_f32_e32 v73, v73
	v_pk_mul_f32 v[64:65], v[64:65], v[68:69]
	v_mul_f32_e32 v68, 0xbfb8aa3b, v70
	v_add_f32_e32 v72, 1.0, v72
	v_add_f32_e32 v73, 1.0, v73
	v_rcp_f32_e32 v72, v72
	v_rcp_f32_e32 v73, v73
	v_mul_f32_e32 v69, 0xbfb8aa3b, v71
	v_exp_f32_e32 v68, v68
	v_exp_f32_e32 v69, v69
	v_pk_mul_f32 v[60:61], v[60:61], v[72:73]
	v_cvt_pk_bf16_f32 v222, v64, v65
	v_pk_mul_f32 v[56:57], v[56:57], v[60:61]
	v_mul_f32_e32 v60, 0xbfb8aa3b, v62
	v_mul_f32_e32 v61, 0xbfb8aa3b, v63
	v_exp_f32_e32 v60, v60
	v_exp_f32_e32 v61, v61
	v_add_f32_e32 v68, 1.0, v68
	v_add_f32_e32 v69, 1.0, v69
	v_rcp_f32_e32 v68, v68
	v_rcp_f32_e32 v69, v69
	v_add_f32_e32 v60, 1.0, v60
	v_add_f32_e32 v61, 1.0, v61
	v_rcp_f32_e32 v60, v60
	v_rcp_f32_e32 v61, v61
	v_pk_mul_f32 v[68:69], v[70:71], v[68:69]
	v_cvt_pk_bf16_f32 v224, v56, v57
	v_pk_mul_f32 v[66:67], v[66:67], v[68:69]
	v_pk_mul_f32 v[60:61], v[62:63], v[60:61]
	v_cvt_pk_bf16_f32 v223, v66, v67
	v_lshl_add_u64 v[66:67], v[144:145], 0, v[242:243]
	s_nop 1
	v_permlane16_swap_b32 v220, v222
	v_permlane16_swap_b32 v221, v223
	global_store_dwordx4 v[66:67], v[220:223], off
	v_add_u32_e32 v64, 0x80, v153
	v_mad_i64_i32 v[70:71], s[34:35], v64, s13, v[136:137]
	v_pk_mul_f32 v[58:59], v[58:59], v[60:61]
	v_add_u32_e32 v64, 0x90, v153
	v_cvt_pk_bf16_f32 v225, v58, v59
	v_mul_f32_e32 v56, 0xbfb8aa3b, v52
	v_mul_f32_e32 v57, 0xbfb8aa3b, v53
	v_exp_f32_e32 v56, v56
	v_exp_f32_e32 v57, v57
	v_mad_i64_i32 v[68:69], s[34:35], v64, s13, v[136:137]
	v_add_f32_e32 v56, 1.0, v56
	v_add_f32_e32 v57, 1.0, v57
	v_rcp_f32_e32 v56, v56
	v_rcp_f32_e32 v57, v57
	v_add_u32_e32 v64, 0xa0, v153
	v_mad_i64_i32 v[66:67], s[34:35], v64, s13, v[136:137]
	v_pk_mul_f32 v[52:53], v[52:53], v[56:57]
	v_add_u32_e32 v64, 0xb0, v153
	v_pk_mul_f32 v[48:49], v[48:49], v[52:53]
	v_mul_f32_e32 v52, 0xbfb8aa3b, v54
	v_mul_f32_e32 v53, 0xbfb8aa3b, v55
	v_exp_f32_e32 v52, v52
	v_exp_f32_e32 v53, v53
	v_cvt_pk_bf16_f32 v226, v48, v49
	v_mad_i64_i32 v[64:65], s[34:35], v64, s13, v[136:137]
	v_add_f32_e32 v52, 1.0, v52
	v_add_f32_e32 v53, 1.0, v53
	v_rcp_f32_e32 v52, v52
	v_rcp_f32_e32 v53, v53
	s_nop 0
	v_pk_mul_f32 v[52:53], v[54:55], v[52:53]
	s_nop 0
	v_pk_mul_f32 v[50:51], v[50:51], v[52:53]
	s_nop 0
	v_cvt_pk_bf16_f32 v227, v50, v51
	v_lshl_add_u64 v[50:51], v[70:71], 0, v[240:241]
	s_nop 1
	v_permlane16_swap_b32 v224, v226
	v_permlane16_swap_b32 v225, v227
	global_store_dwordx4 v[50:51], v[224:227], off
	v_mul_f32_e32 v48, 0xbfb8aa3b, v44
	v_mul_f32_e32 v49, 0xbfb8aa3b, v45
	v_exp_f32_e32 v48, v48
	v_exp_f32_e32 v49, v49
	v_add_f32_e32 v48, 1.0, v48
	v_add_f32_e32 v49, 1.0, v49
	v_rcp_f32_e32 v48, v48
	v_rcp_f32_e32 v49, v49
	s_nop 0
	v_pk_mul_f32 v[44:45], v[44:45], v[48:49]
	s_nop 0
	v_pk_mul_f32 v[40:41], v[40:41], v[44:45]
	v_mul_f32_e32 v44, 0xbfb8aa3b, v46
	v_mul_f32_e32 v45, 0xbfb8aa3b, v47
	v_exp_f32_e32 v44, v44
	v_exp_f32_e32 v45, v45
	v_cvt_pk_bf16_f32 v228, v40, v41
	v_add_f32_e32 v44, 1.0, v44
	v_add_f32_e32 v45, 1.0, v45
	v_rcp_f32_e32 v44, v44
	v_rcp_f32_e32 v45, v45
	s_nop 0
	v_pk_mul_f32 v[44:45], v[46:47], v[44:45]
	s_nop 0
	v_pk_mul_f32 v[42:43], v[42:43], v[44:45]
	s_nop 0
	v_cvt_pk_bf16_f32 v229, v42, v43
	v_mul_f32_e32 v40, 0xbfb8aa3b, v36
	v_mul_f32_e32 v41, 0xbfb8aa3b, v37
	v_exp_f32_e32 v40, v40
	v_exp_f32_e32 v41, v41
	v_add_f32_e32 v40, 1.0, v40
	v_add_f32_e32 v41, 1.0, v41
	v_rcp_f32_e32 v40, v40
	v_rcp_f32_e32 v41, v41
	s_nop 0
	v_pk_mul_f32 v[36:37], v[36:37], v[40:41]
	s_nop 0
	v_pk_mul_f32 v[32:33], v[32:33], v[36:37]
	v_mul_f32_e32 v36, 0xbfb8aa3b, v38
	v_mul_f32_e32 v37, 0xbfb8aa3b, v39
	v_exp_f32_e32 v36, v36
	v_exp_f32_e32 v37, v37
	v_cvt_pk_bf16_f32 v230, v32, v33
	v_add_f32_e32 v36, 1.0, v36
	v_add_f32_e32 v37, 1.0, v37
	v_rcp_f32_e32 v36, v36
	v_rcp_f32_e32 v37, v37
	s_nop 0
	v_pk_mul_f32 v[36:37], v[38:39], v[36:37]
	s_nop 0
	v_pk_mul_f32 v[34:35], v[34:35], v[36:37]
	s_nop 0
	v_cvt_pk_bf16_f32 v231, v34, v35
	v_lshl_add_u64 v[34:35], v[66:67], 0, v[240:241]
	s_nop 1
	v_permlane16_swap_b32 v228, v230
	v_permlane16_swap_b32 v229, v231
	global_store_dwordx4 v[34:35], v[228:231], off
	v_mul_f32_e32 v32, 0xbfb8aa3b, v28
	v_mul_f32_e32 v33, 0xbfb8aa3b, v29
	v_exp_f32_e32 v32, v32
	v_exp_f32_e32 v33, v33
	v_add_f32_e32 v32, 1.0, v32
	v_add_f32_e32 v33, 1.0, v33
	v_rcp_f32_e32 v32, v32
	v_rcp_f32_e32 v33, v33
	s_nop 0
	v_pk_mul_f32 v[28:29], v[28:29], v[32:33]
	s_nop 0
	v_pk_mul_f32 v[24:25], v[24:25], v[28:29]
	v_mul_f32_e32 v28, 0xbfb8aa3b, v30
	v_mul_f32_e32 v29, 0xbfb8aa3b, v31
	v_exp_f32_e32 v28, v28
	v_exp_f32_e32 v29, v29
	v_cvt_pk_bf16_f32 v232, v24, v25
	v_add_f32_e32 v28, 1.0, v28
	v_add_f32_e32 v29, 1.0, v29
	v_rcp_f32_e32 v28, v28
	v_rcp_f32_e32 v29, v29
	s_nop 0
	v_pk_mul_f32 v[28:29], v[30:31], v[28:29]
	s_nop 0
	v_pk_mul_f32 v[26:27], v[26:27], v[28:29]
	s_nop 0
	v_cvt_pk_bf16_f32 v233, v26, v27
	v_mul_f32_e32 v24, 0xbfb8aa3b, v20
	v_mul_f32_e32 v25, 0xbfb8aa3b, v21
	v_exp_f32_e32 v24, v24
	v_exp_f32_e32 v25, v25
	v_add_f32_e32 v24, 1.0, v24
	v_add_f32_e32 v25, 1.0, v25
	v_rcp_f32_e32 v24, v24
	v_rcp_f32_e32 v25, v25
	s_nop 0
	v_pk_mul_f32 v[20:21], v[20:21], v[24:25]
	s_nop 0
	v_pk_mul_f32 v[16:17], v[16:17], v[20:21]
	v_mul_f32_e32 v20, 0xbfb8aa3b, v22
	v_mul_f32_e32 v21, 0xbfb8aa3b, v23
	v_exp_f32_e32 v20, v20
	v_exp_f32_e32 v21, v21
	v_cvt_pk_bf16_f32 v234, v16, v17
	v_add_f32_e32 v20, 1.0, v20
	v_add_f32_e32 v21, 1.0, v21
	v_rcp_f32_e32 v20, v20
	v_rcp_f32_e32 v21, v21
	s_nop 0
	v_pk_mul_f32 v[20:21], v[22:23], v[20:21]
	s_nop 0
	v_pk_mul_f32 v[18:19], v[18:19], v[20:21]
	s_nop 0
	v_cvt_pk_bf16_f32 v235, v18, v19
	v_lshl_add_u64 v[18:19], v[70:71], 0, v[242:243]
	s_nop 1
	v_permlane16_swap_b32 v232, v234
	v_permlane16_swap_b32 v233, v235
	global_store_dwordx4 v[18:19], v[232:235], off
	v_mul_f32_e32 v16, 0xbfb8aa3b, v12
	v_mul_f32_e32 v17, 0xbfb8aa3b, v13
	v_exp_f32_e32 v16, v16
	v_exp_f32_e32 v17, v17
	v_add_f32_e32 v16, 1.0, v16
	v_add_f32_e32 v17, 1.0, v17
	v_rcp_f32_e32 v16, v16
	v_rcp_f32_e32 v17, v17
	s_nop 0
	v_pk_mul_f32 v[12:13], v[12:13], v[16:17]
	s_nop 0
	v_pk_mul_f32 v[8:9], v[8:9], v[12:13]
	v_mul_f32_e32 v12, 0xbfb8aa3b, v14
	v_mul_f32_e32 v13, 0xbfb8aa3b, v15
	v_exp_f32_e32 v12, v12
	v_exp_f32_e32 v13, v13
	v_cvt_pk_bf16_f32 v236, v8, v9
	v_add_f32_e32 v12, 1.0, v12
	v_add_f32_e32 v13, 1.0, v13
	v_rcp_f32_e32 v12, v12
	v_rcp_f32_e32 v13, v13
	s_nop 0
	v_pk_mul_f32 v[12:13], v[14:15], v[12:13]
	s_nop 0
	v_pk_mul_f32 v[10:11], v[10:11], v[12:13]
	s_nop 0
	v_cvt_pk_bf16_f32 v237, v10, v11
	v_mul_f32_e32 v8, 0xbfb8aa3b, v4
	v_mul_f32_e32 v9, 0xbfb8aa3b, v5
	v_exp_f32_e32 v8, v8
	v_exp_f32_e32 v9, v9
	v_add_f32_e32 v8, 1.0, v8
	v_add_f32_e32 v9, 1.0, v9
	v_rcp_f32_e32 v8, v8
	v_rcp_f32_e32 v9, v9
	s_nop 0
	v_pk_mul_f32 v[4:5], v[4:5], v[8:9]
	s_nop 0
	v_pk_mul_f32 v[0:1], v[0:1], v[4:5]
	v_mul_f32_e32 v4, 0xbfb8aa3b, v6
	v_mul_f32_e32 v5, 0xbfb8aa3b, v7
	v_exp_f32_e32 v4, v4
	v_exp_f32_e32 v5, v5
	v_cvt_pk_bf16_f32 v238, v0, v1
	v_add_f32_e32 v4, 1.0, v4
	v_add_f32_e32 v5, 1.0, v5
	v_rcp_f32_e32 v4, v4
	v_rcp_f32_e32 v5, v5
	s_nop 0
	v_pk_mul_f32 v[4:5], v[6:7], v[4:5]
	s_nop 0
	v_pk_mul_f32 v[2:3], v[2:3], v[4:5]
	s_nop 0
	v_cvt_pk_bf16_f32 v239, v2, v3
	v_lshl_add_u64 v[2:3], v[66:67], 0, v[242:243]
	s_nop 1
	v_permlane16_swap_b32 v236, v238
	v_permlane16_swap_b32 v237, v239
	global_store_dwordx4 v[2:3], v[236:239], off
	s_cbranch_vccz .LBB0_1970
